# weight conversion items: the 8 dependent norm-weight loads issued together behind the row loads (one round trip per item)
# speedup vs baseline: 1.0063x; 1.0063x over previous
; __device__ __forceinline__ void transpose_item(const float* W, int K, int N, bf16* WT, const float* scale, LAS float* scr, int item, int lane) {
;     const int nblk = N / 32, kb = item / nblk, nb = item % nblk, k0 = 64 * kb, n0 = 32 * nb;
;     {
;         const int q = lane & 7, r = lane >> 3;
;         f32x4 v[8];
; #pragma unroll
;         for (int i = 0; i < 8; ++i) v[i] = *(const f32x4*)(W + (size_t)(k0 + 8 * i + r) * N + n0 + 4 * q);
; #pragma unroll
;         for (int i = 0; i < 8; ++i) { const int kk = 8 * i + r; f32x4 x = v[i]; if (scale) x = x * scale[k0 + kk];
;             scr[kk * 33 + 4 * q + 0] = x[0]; scr[kk * 33 + 4 * q + 1] = x[1]; scr[kk * 33 + 4 * q + 2] = x[2]; scr[kk * 33 + 4 * q + 3] = x[3]; }
.LBB0_1263:
	s_mul_hi_i32 s0, s6, 0x66666667
	s_lshr_b32 s1, s0, 31
	s_ashr_i32 s0, s0, 7
	s_add_i32 s0, s0, s1
	s_lshl_b32 s2, s0, 6
	s_mulk_i32 s0, 0xd800
	s_add_i32 s0, s4, s0
	s_ashr_i32 s1, s0, 31
	s_waitcnt vmcnt(1)
	v_or_b32_e32 v48, s2, v1
	v_lshl_add_u64 v[2:3], s[0:1], 2, v[22:23]
	v_mad_i64_i32 v[4:5], s[8:9], v48, s12, v[2:3]
	global_load_dwordx4 v[36:39], v[4:5], off nt
	v_or_b32_e32 v4, 8, v48
	v_mad_i64_i32 v[4:5], s[8:9], v4, s12, v[2:3]
	global_load_dwordx4 v[40:43], v[4:5], off nt
	v_or_b32_e32 v4, 16, v48
	v_mad_i64_i32 v[4:5], s[8:9], v4, s12, v[2:3]
	global_load_dwordx4 v[44:47], v[4:5], off nt
	v_or_b32_e32 v4, 24, v48
	v_mad_i64_i32 v[4:5], s[8:9], v4, s12, v[2:3]
	global_load_dwordx4 v[18:21], v[4:5], off nt
	v_or_b32_e32 v4, 32, v48
	v_mad_i64_i32 v[4:5], s[8:9], v4, s12, v[2:3]
	global_load_dwordx4 v[14:17], v[4:5], off nt
	v_or_b32_e32 v4, 40, v48
	v_mad_i64_i32 v[4:5], s[8:9], v4, s12, v[2:3]
	global_load_dwordx4 v[10:13], v[4:5], off nt
	v_or_b32_e32 v4, 48, v48
	v_ashrrev_i32_e32 v49, 31, v48
	v_mad_i64_i32 v[4:5], s[8:9], v4, s12, v[2:3]
	global_load_dwordx4 v[6:9], v[4:5], off nt
	v_or_b32_e32 v4, 56, v48
	v_lshl_add_u64 v[48:49], v[48:49], 2, s[10:11]
	global_load_dword v48, v[48:49], off
	v_mad_i64_i32 v[2:3], s[8:9], v4, s12, v[2:3]
	global_load_dwordx4 v[2:5], v[2:3], off nt
	v_or_b32_e32 v202, s2, v26
	v_ashrrev_i32_e32 v203, 31, v202
	v_lshl_add_u64 v[202:203], v[202:203], 2, s[10:11]
	global_load_dword v221, v[202:203], off
	v_or_b32_e32 v204, s2, v27
	v_ashrrev_i32_e32 v205, 31, v204
	v_lshl_add_u64 v[204:205], v[204:205], 2, s[10:11]
	global_load_dword v222, v[204:205], off
	v_or_b32_e32 v206, s2, v28
	v_ashrrev_i32_e32 v207, 31, v206
	v_lshl_add_u64 v[206:207], v[206:207], 2, s[10:11]
	global_load_dword v223, v[206:207], off
	v_or_b32_e32 v208, s2, v29
	v_ashrrev_i32_e32 v209, 31, v208
	v_lshl_add_u64 v[208:209], v[208:209], 2, s[10:11]
	global_load_dword v224, v[208:209], off
	v_or_b32_e32 v210, s2, v30
	v_ashrrev_i32_e32 v211, 31, v210
	v_lshl_add_u64 v[210:211], v[210:211], 2, s[10:11]
	global_load_dword v225, v[210:211], off
	v_or_b32_e32 v212, s2, v31
	v_ashrrev_i32_e32 v213, 31, v212
	v_lshl_add_u64 v[212:213], v[212:213], 2, s[10:11]
	global_load_dword v226, v[212:213], off
	v_or_b32_e32 v214, s2, v32
	v_ashrrev_i32_e32 v215, 31, v214
	v_lshl_add_u64 v[214:215], v[214:215], 2, s[10:11]
	global_load_dword v227, v[214:215], off
	v_add_u32_e32 v35, 0x420, v34
	s_ashr_i32 s3, s2, 31
	s_add_i32 s6, s6, s7
	s_add_i32 s4, s4, s5
	s_cmpk_lt_i32 s6, 0x1400
	s_waitcnt vmcnt(8)
	v_pk_mul_f32 v[36:37], v[36:37], v[48:49] op_sel_hi:[1,0]
	v_pk_mul_f32 v[38:39], v[38:39], v[48:49] op_sel_hi:[1,0]
	ds_write2_b32 v34, v36, v37 offset1:1
	ds_write2_b32 v34, v38, v39 offset0:2 offset1:3
	v_or_b32_e32 v36, s2, v26
	v_ashrrev_i32_e32 v37, 31, v36
	v_lshl_add_u64 v[36:37], v[36:37], 2, s[10:11]
	s_waitcnt vmcnt(6)
	v_mov_b32_e32 v36, v221
	s_waitcnt vmcnt(0)
	v_pk_mul_f32 v[38:39], v[42:43], v[36:37] op_sel_hi:[1,0]
	v_pk_mul_f32 v[36:37], v[40:41], v[36:37] op_sel_hi:[1,0]
	ds_write2_b32 v35, v36, v37 offset1:1
	v_or_b32_e32 v36, s2, v27
	v_ashrrev_i32_e32 v37, 31, v36
	v_lshl_add_u64 v[36:37], v[36:37], 2, s[10:11]
	s_waitcnt vmcnt(5)
	v_mov_b32_e32 v36, v222
	v_add_u32_e32 v35, 0x428, v34
	ds_write2_b32 v35, v38, v39 offset1:1
	v_add_u32_e32 v35, 0x840, v34
	s_waitcnt vmcnt(0)
	v_pk_mul_f32 v[38:39], v[46:47], v[36:37] op_sel_hi:[1,0]
	v_pk_mul_f32 v[36:37], v[44:45], v[36:37] op_sel_hi:[1,0]
	ds_write2_b32 v35, v36, v37 offset1:1
	v_or_b32_e32 v36, s2, v28
	v_ashrrev_i32_e32 v37, 31, v36
	v_lshl_add_u64 v[36:37], v[36:37], 2, s[10:11]
	s_waitcnt vmcnt(4)
	v_mov_b32_e32 v36, v223
	v_add_u32_e32 v35, 0x848, v34
	ds_write2_b32 v35, v38, v39 offset1:1
	v_add_u32_e32 v35, 0xc60, v34
	v_add_u32_e32 v38, s0, v1
	v_ashrrev_i32_e32 v39, 31, v38
	v_lshlrev_b64 v[40:41], 11, v[38:39]
	s_waitcnt vmcnt(0)
; #define LAS __attribute__((address_space(3)))
; __device__ __forceinline__ unsigned pk2(float lo, float hi) { f32x2_t v = {lo, hi}; bf16x2_t b = __builtin_convertvector(v, bf16x2_t); return __builtin_bit_cast(unsigned, b); }
; __device__ __forceinline__ void transpose_item(const float* W, int K, int N, bf16* WT, const float* scale, LAS float* scr, int item, int lane) {
;     ...
;         for (int i = 0; i < 8; ++i) { const int kk = 8 * i + r; f32x4 x = v[i]; if (scale) x = x * scale[k0 + kk];
;             scr[kk * 33 + 4 * q + 0] = x[0]; scr[kk * 33 + 4 * q + 1] = x[1]; scr[kk * 33 + 4 * q + 2] = x[2]; scr[kk * 33 + 4 * q + 3] = x[3]; }
;     }
;     asm volatile("s_waitcnt lgkmcnt(0)" ::: "memory");
;     const int c = lane & 7;
; #pragma unroll
;     for (int j = 0; j < 4; ++j) { const int n = (lane >> 3) + 8 * j; const LAS float* s = scr + (8 * c) * 33 + n;
;         v4u o; o.x = pk2(s[0 * 33], s[1 * 33]); o.y = pk2(s[2 * 33], s[3 * 33]); o.z = pk2(s[4 * 33], s[5 * 33]); o.w = pk2(s[6 * 33], s[7 * 33]);
;         *(v4u*)(WT + (size_t)(n0 + n) * K + k0 + 8 * c) = o; }
	v_pk_mul_f32 v[18:19], v[18:19], v[36:37] op_sel_hi:[1,0]
	v_pk_mul_f32 v[20:21], v[20:21], v[36:37] op_sel_hi:[1,0]
	ds_write2_b32 v35, v18, v19 offset1:1
	v_add_u32_e32 v18, 0xc68, v34
	ds_write2_b32 v18, v20, v21 offset1:1
	v_or_b32_e32 v18, s2, v29
	v_ashrrev_i32_e32 v19, 31, v18
	v_lshl_add_u64 v[18:19], v[18:19], 2, s[10:11]
	s_waitcnt vmcnt(3)
	v_mov_b32_e32 v18, v224
	s_waitcnt vmcnt(0)
	v_pk_mul_f32 v[16:17], v[16:17], v[18:19] op_sel_hi:[1,0]
	v_pk_mul_f32 v[14:15], v[14:15], v[18:19] op_sel_hi:[1,0]
	v_add_u32_e32 v18, 0x1080, v34
	ds_write2_b32 v18, v14, v15 offset1:1
	v_add_u32_e32 v14, 0x1088, v34
	ds_write2_b32 v14, v16, v17 offset1:1
	v_or_b32_e32 v14, s2, v30
	v_ashrrev_i32_e32 v15, 31, v14
	v_lshl_add_u64 v[14:15], v[14:15], 2, s[10:11]
	s_waitcnt vmcnt(2)
	v_mov_b32_e32 v14, v225
	s_waitcnt vmcnt(0)
	v_pk_mul_f32 v[12:13], v[12:13], v[14:15] op_sel_hi:[1,0]
	v_pk_mul_f32 v[10:11], v[10:11], v[14:15] op_sel_hi:[1,0]
	v_add_u32_e32 v14, 0x14a0, v34
	ds_write2_b32 v14, v10, v11 offset1:1
	v_add_u32_e32 v10, 0x14a8, v34
	ds_write2_b32 v10, v12, v13 offset1:1
	v_or_b32_e32 v10, s2, v31
	v_ashrrev_i32_e32 v11, 31, v10
	v_lshl_add_u64 v[10:11], v[10:11], 2, s[10:11]
	s_waitcnt vmcnt(1)
	v_mov_b32_e32 v10, v226
	s_waitcnt vmcnt(0)
	v_pk_mul_f32 v[8:9], v[8:9], v[10:11] op_sel_hi:[1,0]
	v_pk_mul_f32 v[6:7], v[6:7], v[10:11] op_sel_hi:[1,0]
	v_add_u32_e32 v10, 0x18c0, v34
	ds_write2_b32 v10, v6, v7 offset1:1
	v_add_u32_e32 v6, 0x18c8, v34
	ds_write2_b32 v6, v8, v9 offset1:1
	v_or_b32_e32 v6, s2, v32
	v_ashrrev_i32_e32 v7, 31, v6
	v_lshl_add_u64 v[6:7], v[6:7], 2, s[10:11]
	s_waitcnt vmcnt(0)
	v_mov_b32_e32 v6, v227
	s_waitcnt vmcnt(0)
	v_pk_mul_f32 v[4:5], v[4:5], v[6:7] op_sel_hi:[1,0]
	v_pk_mul_f32 v[2:3], v[2:3], v[6:7] op_sel_hi:[1,0]
	v_add_u32_e32 v6, 0x1ce0, v34
	ds_write2_b32 v6, v2, v3 offset1:1
	v_add_u32_e32 v2, 0x1ce8, v34
	ds_write2_b32 v2, v4, v5 offset1:1
	s_waitcnt lgkmcnt(0)
	ds_read2_b32 v[8:9], v33 offset0:33 offset1:41
	ds_read2_b32 v[10:11], v33 offset1:8
	ds_read2_b32 v[12:13], v33 offset0:66 offset1:74
	ds_read2_b32 v[14:15], v33 offset0:99 offset1:107
	ds_read2_b32 v[16:17], v33 offset0:132 offset1:140
	ds_read2_b32 v[18:19], v33 offset0:165 offset1:173
	ds_read2_b32 v[20:21], v33 offset0:198 offset1:206
	ds_read2_b32 v[36:37], v33 offset0:231 offset1:239
	v_lshl_add_u64 v[6:7], s[2:3], 1, v[24:25]
	s_waitcnt lgkmcnt(6)
	v_cvt_pk_bf16_f32 v2, v10, v8
	s_waitcnt lgkmcnt(4)
	v_cvt_pk_bf16_f32 v3, v12, v14
	s_waitcnt lgkmcnt(2)
	v_cvt_pk_bf16_f32 v4, v16, v18
	s_waitcnt lgkmcnt(0)
	v_cvt_pk_bf16_f32 v5, v20, v36
	v_lshl_add_u64 v[40:41], v[6:7], 0, v[40:41]
	v_add_u32_e32 v8, 8, v38
	global_store_dwordx4 v[40:41], v[2:5], off nt
	v_add_u32_e32 v40, 16, v38
	v_ashrrev_i32_e32 v41, 31, v40
	v_cvt_pk_bf16_f32 v2, v11, v9
	v_ashrrev_i32_e32 v9, 31, v8
	v_lshlrev_b64 v[8:9], 11, v[8:9]
	v_cvt_pk_bf16_f32 v3, v13, v15
	v_cvt_pk_bf16_f32 v4, v17, v19
	v_cvt_pk_bf16_f32 v5, v21, v37
	v_lshl_add_u64 v[8:9], v[6:7], 0, v[8:9]
	global_store_dwordx4 v[8:9], v[2:5], off nt
	ds_read2_b32 v[8:9], v33 offset0:49 offset1:57
	ds_read2_b32 v[10:11], v33 offset0:16 offset1:24
	ds_read2_b32 v[12:13], v33 offset0:82 offset1:90
	ds_read2_b32 v[14:15], v33 offset0:115 offset1:123
	ds_read2_b32 v[16:17], v33 offset0:148 offset1:156
	ds_read2_b32 v[18:19], v33 offset0:181 offset1:189
	ds_read2_b32 v[20:21], v33 offset0:214 offset1:222
	ds_read2_b32 v[36:37], v33 offset0:247 offset1:255
	v_lshlrev_b64 v[40:41], 11, v[40:41]
	s_waitcnt lgkmcnt(6)
	v_cvt_pk_bf16_f32 v2, v10, v8
	s_waitcnt lgkmcnt(4)
	v_cvt_pk_bf16_f32 v3, v12, v14
	s_waitcnt lgkmcnt(2)
	v_cvt_pk_bf16_f32 v4, v16, v18
	s_waitcnt lgkmcnt(0)
	v_cvt_pk_bf16_f32 v5, v20, v36
	v_lshl_add_u64 v[40:41], v[6:7], 0, v[40:41]
	v_add_u32_e32 v8, 24, v38
	global_store_dwordx4 v[40:41], v[2:5], off nt
	s_nop 1
	v_cvt_pk_bf16_f32 v2, v11, v9
	v_ashrrev_i32_e32 v9, 31, v8
	v_lshlrev_b64 v[8:9], 11, v[8:9]
	v_cvt_pk_bf16_f32 v3, v13, v15
	v_cvt_pk_bf16_f32 v4, v17, v19
	v_cvt_pk_bf16_f32 v5, v21, v37
	v_lshl_add_u64 v[6:7], v[6:7], 0, v[8:9]
	global_store_dwordx4 v[6:7], v[2:5], off nt
	s_waitcnt lgkmcnt(0)
	s_cbranch_scc1 .LBB0_1263

; __device__ __forceinline__ void transpose_item(const float* W, int K, int N, bf16* WT, const float* scale, LAS float* scr, int item, int lane) {
;     const int nblk = N / 32, kb = item / nblk, nb = item % nblk, k0 = 64 * kb, n0 = 32 * nb;
;     {
;         const int q = lane & 7, r = lane >> 3;
;         f32x4 v[8];
; #pragma unroll
;         for (int i = 0; i < 8; ++i) v[i] = *(const f32x4*)(W + (size_t)(k0 + 8 * i + r) * N + n0 + 4 * q);
; #pragma unroll
;         for (int i = 0; i < 8; ++i) { const int kk = 8 * i + r; f32x4 x = v[i]; if (scale) x = x * scale[k0 + kk];
;             scr[kk * 33 + 4 * q + 0] = x[0]; scr[kk * 33 + 4 * q + 1] = x[1]; scr[kk * 33 + 4 * q + 2] = x[2]; scr[kk * 33 + 4 * q + 3] = x[3]; }
.LBB0_1270:
	s_mul_hi_i32 s2, s8, 0x2aaaaaab
	s_lshr_b32 s3, s2, 31
	s_ashr_i32 s2, s2, 4
	s_add_i32 s2, s2, s3
	s_lshl_b32 s4, s2, 6
	s_mulk_i32 s2, 0xf400
	s_add_i32 s2, s6, s2
	s_ashr_i32 s3, s2, 31
	s_waitcnt vmcnt(1)
	v_or_b32_e32 v48, s4, v1
	v_lshl_add_u64 v[2:3], s[2:3], 2, v[22:23]
	v_mad_i64_i32 v[4:5], s[10:11], v48, s14, v[2:3]
	global_load_dwordx4 v[36:39], v[4:5], off nt
	v_or_b32_e32 v4, 8, v48
	v_mad_i64_i32 v[4:5], s[10:11], v4, s14, v[2:3]
	global_load_dwordx4 v[40:43], v[4:5], off nt
	v_or_b32_e32 v4, 16, v48
	v_mad_i64_i32 v[4:5], s[10:11], v4, s14, v[2:3]
	global_load_dwordx4 v[44:47], v[4:5], off nt
	v_or_b32_e32 v4, 24, v48
	v_mad_i64_i32 v[4:5], s[10:11], v4, s14, v[2:3]
	global_load_dwordx4 v[18:21], v[4:5], off nt
	v_or_b32_e32 v4, 32, v48
	v_mad_i64_i32 v[4:5], s[10:11], v4, s14, v[2:3]
	global_load_dwordx4 v[14:17], v[4:5], off nt
	v_or_b32_e32 v4, 40, v48
	v_mad_i64_i32 v[4:5], s[10:11], v4, s14, v[2:3]
	global_load_dwordx4 v[10:13], v[4:5], off nt
	v_or_b32_e32 v4, 48, v48
	v_ashrrev_i32_e32 v49, 31, v48
	v_mad_i64_i32 v[4:5], s[10:11], v4, s14, v[2:3]
	global_load_dwordx4 v[6:9], v[4:5], off nt
	v_or_b32_e32 v4, 56, v48
	v_lshl_add_u64 v[48:49], v[48:49], 2, s[12:13]
	global_load_dword v48, v[48:49], off
	v_mad_i64_i32 v[2:3], s[10:11], v4, s14, v[2:3]
	global_load_dwordx4 v[2:5], v[2:3], off nt
	v_or_b32_e32 v202, s4, v26
	v_ashrrev_i32_e32 v203, 31, v202
	v_lshl_add_u64 v[202:203], v[202:203], 2, s[12:13]
	global_load_dword v221, v[202:203], off
	v_or_b32_e32 v204, s4, v27
	v_ashrrev_i32_e32 v205, 31, v204
	v_lshl_add_u64 v[204:205], v[204:205], 2, s[12:13]
	global_load_dword v222, v[204:205], off
	v_or_b32_e32 v206, s4, v28
	v_ashrrev_i32_e32 v207, 31, v206
	v_lshl_add_u64 v[206:207], v[206:207], 2, s[12:13]
	global_load_dword v223, v[206:207], off
	v_or_b32_e32 v208, s4, v29
	v_ashrrev_i32_e32 v209, 31, v208
	v_lshl_add_u64 v[208:209], v[208:209], 2, s[12:13]
	global_load_dword v224, v[208:209], off
	v_or_b32_e32 v210, s4, v30
	v_ashrrev_i32_e32 v211, 31, v210
	v_lshl_add_u64 v[210:211], v[210:211], 2, s[12:13]
	global_load_dword v225, v[210:211], off
	v_or_b32_e32 v212, s4, v31
	v_ashrrev_i32_e32 v213, 31, v212
	v_lshl_add_u64 v[212:213], v[212:213], 2, s[12:13]
	global_load_dword v226, v[212:213], off
	v_or_b32_e32 v214, s4, v32
	v_ashrrev_i32_e32 v215, 31, v214
	v_lshl_add_u64 v[214:215], v[214:215], 2, s[12:13]
	global_load_dword v227, v[214:215], off
	v_add_u32_e32 v35, 0x420, v34
	s_ashr_i32 s5, s4, 31
	s_add_i32 s8, s8, s9
	s_add_i32 s6, s6, s7
	s_cmpk_lt_i32 s8, 0x600
	s_waitcnt vmcnt(8)
	v_pk_mul_f32 v[36:37], v[36:37], v[48:49] op_sel_hi:[1,0]
	v_pk_mul_f32 v[38:39], v[38:39], v[48:49] op_sel_hi:[1,0]
	ds_write2_b32 v34, v36, v37 offset1:1
	ds_write2_b32 v34, v38, v39 offset0:2 offset1:3
	v_or_b32_e32 v36, s4, v26
	v_ashrrev_i32_e32 v37, 31, v36
	v_lshl_add_u64 v[36:37], v[36:37], 2, s[12:13]
	s_waitcnt vmcnt(6)
	v_mov_b32_e32 v36, v221
	s_waitcnt vmcnt(0)
	v_pk_mul_f32 v[38:39], v[42:43], v[36:37] op_sel_hi:[1,0]
	v_pk_mul_f32 v[36:37], v[40:41], v[36:37] op_sel_hi:[1,0]
	ds_write2_b32 v35, v36, v37 offset1:1
	v_or_b32_e32 v36, s4, v27
	v_ashrrev_i32_e32 v37, 31, v36
	v_lshl_add_u64 v[36:37], v[36:37], 2, s[12:13]
	s_waitcnt vmcnt(5)
	v_mov_b32_e32 v36, v222
	v_add_u32_e32 v35, 0x428, v34
	ds_write2_b32 v35, v38, v39 offset1:1
	v_add_u32_e32 v35, 0x840, v34
	s_waitcnt vmcnt(0)
	v_pk_mul_f32 v[38:39], v[46:47], v[36:37] op_sel_hi:[1,0]
	v_pk_mul_f32 v[36:37], v[44:45], v[36:37] op_sel_hi:[1,0]
	ds_write2_b32 v35, v36, v37 offset1:1
	v_or_b32_e32 v36, s4, v28
	v_ashrrev_i32_e32 v37, 31, v36
	v_lshl_add_u64 v[36:37], v[36:37], 2, s[12:13]
	s_waitcnt vmcnt(4)
	v_mov_b32_e32 v36, v223
	v_add_u32_e32 v35, 0x848, v34
	ds_write2_b32 v35, v38, v39 offset1:1
	v_add_u32_e32 v35, 0xc60, v34
	v_add_u32_e32 v38, s2, v1
	v_ashrrev_i32_e32 v39, 31, v38
	v_lshlrev_b64 v[40:41], 11, v[38:39]
	s_waitcnt vmcnt(0)
; #define LAS __attribute__((address_space(3)))
; __device__ __forceinline__ unsigned pk2(float lo, float hi) { f32x2_t v = {lo, hi}; bf16x2_t b = __builtin_convertvector(v, bf16x2_t); return __builtin_bit_cast(unsigned, b); }
; __device__ __forceinline__ void transpose_item(const float* W, int K, int N, bf16* WT, const float* scale, LAS float* scr, int item, int lane) {
;     ...
;         for (int i = 0; i < 8; ++i) { const int kk = 8 * i + r; f32x4 x = v[i]; if (scale) x = x * scale[k0 + kk];
;             scr[kk * 33 + 4 * q + 0] = x[0]; scr[kk * 33 + 4 * q + 1] = x[1]; scr[kk * 33 + 4 * q + 2] = x[2]; scr[kk * 33 + 4 * q + 3] = x[3]; }
;     }
;     asm volatile("s_waitcnt lgkmcnt(0)" ::: "memory");
;     const int c = lane & 7;
; #pragma unroll
;     for (int j = 0; j < 4; ++j) { const int n = (lane >> 3) + 8 * j; const LAS float* s = scr + (8 * c) * 33 + n;
;         v4u o; o.x = pk2(s[0 * 33], s[1 * 33]); o.y = pk2(s[2 * 33], s[3 * 33]); o.z = pk2(s[4 * 33], s[5 * 33]); o.w = pk2(s[6 * 33], s[7 * 33]);
;         *(v4u*)(WT + (size_t)(n0 + n) * K + k0 + 8 * c) = o; }
	v_pk_mul_f32 v[18:19], v[18:19], v[36:37] op_sel_hi:[1,0]
	v_pk_mul_f32 v[20:21], v[20:21], v[36:37] op_sel_hi:[1,0]
	ds_write2_b32 v35, v18, v19 offset1:1
	v_add_u32_e32 v18, 0xc68, v34
	ds_write2_b32 v18, v20, v21 offset1:1
	v_or_b32_e32 v18, s4, v29
	v_ashrrev_i32_e32 v19, 31, v18
	v_lshl_add_u64 v[18:19], v[18:19], 2, s[12:13]
	s_waitcnt vmcnt(3)
	v_mov_b32_e32 v18, v224
	s_waitcnt vmcnt(0)
	v_pk_mul_f32 v[16:17], v[16:17], v[18:19] op_sel_hi:[1,0]
	v_pk_mul_f32 v[14:15], v[14:15], v[18:19] op_sel_hi:[1,0]
	v_add_u32_e32 v18, 0x1080, v34
	ds_write2_b32 v18, v14, v15 offset1:1
	v_add_u32_e32 v14, 0x1088, v34
	ds_write2_b32 v14, v16, v17 offset1:1
	v_or_b32_e32 v14, s4, v30
	v_ashrrev_i32_e32 v15, 31, v14
	v_lshl_add_u64 v[14:15], v[14:15], 2, s[12:13]
	s_waitcnt vmcnt(2)
	v_mov_b32_e32 v14, v225
	s_waitcnt vmcnt(0)
	v_pk_mul_f32 v[12:13], v[12:13], v[14:15] op_sel_hi:[1,0]
	v_pk_mul_f32 v[10:11], v[10:11], v[14:15] op_sel_hi:[1,0]
	v_add_u32_e32 v14, 0x14a0, v34
	ds_write2_b32 v14, v10, v11 offset1:1
	v_add_u32_e32 v10, 0x14a8, v34
	ds_write2_b32 v10, v12, v13 offset1:1
	v_or_b32_e32 v10, s4, v31
	v_ashrrev_i32_e32 v11, 31, v10
	v_lshl_add_u64 v[10:11], v[10:11], 2, s[12:13]
	s_waitcnt vmcnt(1)
	v_mov_b32_e32 v10, v226
	s_waitcnt vmcnt(0)
	v_pk_mul_f32 v[8:9], v[8:9], v[10:11] op_sel_hi:[1,0]
	v_pk_mul_f32 v[6:7], v[6:7], v[10:11] op_sel_hi:[1,0]
	v_add_u32_e32 v10, 0x18c0, v34
	ds_write2_b32 v10, v6, v7 offset1:1
	v_add_u32_e32 v6, 0x18c8, v34
	ds_write2_b32 v6, v8, v9 offset1:1
	v_or_b32_e32 v6, s4, v32
	v_ashrrev_i32_e32 v7, 31, v6
	v_lshl_add_u64 v[6:7], v[6:7], 2, s[12:13]
	s_waitcnt vmcnt(0)
	v_mov_b32_e32 v6, v227
	s_waitcnt vmcnt(0)
	v_pk_mul_f32 v[4:5], v[4:5], v[6:7] op_sel_hi:[1,0]
	v_pk_mul_f32 v[2:3], v[2:3], v[6:7] op_sel_hi:[1,0]
	v_add_u32_e32 v6, 0x1ce0, v34
	ds_write2_b32 v6, v2, v3 offset1:1
	v_add_u32_e32 v2, 0x1ce8, v34
	ds_write2_b32 v2, v4, v5 offset1:1
	s_waitcnt lgkmcnt(0)
	ds_read2_b32 v[8:9], v33 offset0:33 offset1:41
	ds_read2_b32 v[10:11], v33 offset1:8
	ds_read2_b32 v[12:13], v33 offset0:66 offset1:74
	ds_read2_b32 v[14:15], v33 offset0:99 offset1:107
	ds_read2_b32 v[16:17], v33 offset0:132 offset1:140
	ds_read2_b32 v[18:19], v33 offset0:165 offset1:173
	ds_read2_b32 v[20:21], v33 offset0:198 offset1:206
	ds_read2_b32 v[36:37], v33 offset0:231 offset1:239
	v_lshl_add_u64 v[6:7], s[4:5], 1, v[24:25]
	s_waitcnt lgkmcnt(6)
	v_cvt_pk_bf16_f32 v2, v10, v8
	s_waitcnt lgkmcnt(4)
	v_cvt_pk_bf16_f32 v3, v12, v14
	s_waitcnt lgkmcnt(2)
	v_cvt_pk_bf16_f32 v4, v16, v18
	s_waitcnt lgkmcnt(0)
	v_cvt_pk_bf16_f32 v5, v20, v36
	v_lshl_add_u64 v[40:41], v[6:7], 0, v[40:41]
	v_add_u32_e32 v8, 8, v38
	global_store_dwordx4 v[40:41], v[2:5], off nt
	v_add_u32_e32 v40, 16, v38
	v_ashrrev_i32_e32 v41, 31, v40
	v_cvt_pk_bf16_f32 v2, v11, v9
	v_ashrrev_i32_e32 v9, 31, v8
	v_lshlrev_b64 v[8:9], 11, v[8:9]
	v_cvt_pk_bf16_f32 v3, v13, v15
	v_cvt_pk_bf16_f32 v4, v17, v19
	v_cvt_pk_bf16_f32 v5, v21, v37
	v_lshl_add_u64 v[8:9], v[6:7], 0, v[8:9]
	global_store_dwordx4 v[8:9], v[2:5], off nt
	ds_read2_b32 v[8:9], v33 offset0:49 offset1:57
	ds_read2_b32 v[10:11], v33 offset0:16 offset1:24
	ds_read2_b32 v[12:13], v33 offset0:82 offset1:90
	ds_read2_b32 v[14:15], v33 offset0:115 offset1:123
	ds_read2_b32 v[16:17], v33 offset0:148 offset1:156
	ds_read2_b32 v[18:19], v33 offset0:181 offset1:189
	ds_read2_b32 v[20:21], v33 offset0:214 offset1:222
	ds_read2_b32 v[36:37], v33 offset0:247 offset1:255
	v_lshlrev_b64 v[40:41], 11, v[40:41]
	s_waitcnt lgkmcnt(6)
	v_cvt_pk_bf16_f32 v2, v10, v8
	s_waitcnt lgkmcnt(4)
	v_cvt_pk_bf16_f32 v3, v12, v14
	s_waitcnt lgkmcnt(2)
	v_cvt_pk_bf16_f32 v4, v16, v18
	s_waitcnt lgkmcnt(0)
	v_cvt_pk_bf16_f32 v5, v20, v36
	v_lshl_add_u64 v[40:41], v[6:7], 0, v[40:41]
	v_add_u32_e32 v8, 24, v38
	global_store_dwordx4 v[40:41], v[2:5], off nt
	s_nop 1
	v_cvt_pk_bf16_f32 v2, v11, v9
	v_ashrrev_i32_e32 v9, 31, v8
	v_lshlrev_b64 v[8:9], 11, v[8:9]
	v_cvt_pk_bf16_f32 v3, v13, v15
	v_cvt_pk_bf16_f32 v4, v17, v19
	v_cvt_pk_bf16_f32 v5, v21, v37
	v_lshl_add_u64 v[6:7], v[6:7], 0, v[8:9]
	global_store_dwordx4 v[6:7], v[2:5], off nt
	s_waitcnt lgkmcnt(0)
	s_cbranch_scc1 .LBB0_1270
	v_readlane_b32 s50, v255, 24
	v_readlane_b32 s51, v255, 25

; __device__ __forceinline__ void transpose_item(const float* W, int K, int N, bf16* WT, const float* scale, LAS float* scr, int item, int lane) {
;     const int nblk = N / 32, kb = item / nblk, nb = item % nblk, k0 = 64 * kb, n0 = 32 * nb;
;     {
;         const int q = lane & 7, r = lane >> 3;
;         f32x4 v[8];
; #pragma unroll
;         for (int i = 0; i < 8; ++i) v[i] = *(const f32x4*)(W + (size_t)(k0 + 8 * i + r) * N + n0 + 4 * q);
; #pragma unroll
;         for (int i = 0; i < 8; ++i) { const int kk = 8 * i + r; f32x4 x = v[i]; if (scale) x = x * scale[k0 + kk];
;             scr[kk * 33 + 4 * q + 0] = x[0]; scr[kk * 33 + 4 * q + 1] = x[1]; scr[kk * 33 + 4 * q + 2] = x[2]; scr[kk * 33 + 4 * q + 3] = x[3]; }
.LBB0_1278:
	s_ashr_i32 s0, s6, 31
	s_lshr_b32 s0, s0, 25
	s_add_i32 s0, s6, s0
	s_ashr_i32 s0, s0, 7
	s_lshl_b32 s2, s0, 6
	s_lshl_b32 s0, s0, 12
	s_sub_i32 s0, s4, s0
	s_waitcnt vmcnt(1)
	v_or_b32_e32 v48, s2, v1
	s_ashr_i32 s1, s0, 31
	v_ashrrev_i32_e32 v49, 31, v48
	v_lshl_add_u64 v[2:3], s[0:1], 2, v[26:27]
	v_lshlrev_b64 v[4:5], 14, v[48:49]
	v_lshl_add_u64 v[4:5], v[2:3], 0, v[4:5]
	global_load_dwordx4 v[30:33], v[4:5], off nt
	v_or_b32_e32 v4, 8, v48
	v_ashrrev_i32_e32 v5, 31, v4
	v_lshlrev_b64 v[4:5], 14, v[4:5]
	v_lshl_add_u64 v[4:5], v[2:3], 0, v[4:5]
	global_load_dwordx4 v[44:47], v[4:5], off nt
	v_or_b32_e32 v4, 16, v48
	v_ashrrev_i32_e32 v5, 31, v4
	v_lshlrev_b64 v[4:5], 14, v[4:5]
	v_lshl_add_u64 v[4:5], v[2:3], 0, v[4:5]
	global_load_dwordx4 v[22:25], v[4:5], off nt
	v_or_b32_e32 v4, 24, v48
	v_ashrrev_i32_e32 v5, 31, v4
	v_lshlrev_b64 v[4:5], 14, v[4:5]
	v_lshl_add_u64 v[4:5], v[2:3], 0, v[4:5]
	global_load_dwordx4 v[18:21], v[4:5], off nt
	v_or_b32_e32 v4, 32, v48
	v_ashrrev_i32_e32 v5, 31, v4
	v_lshlrev_b64 v[4:5], 14, v[4:5]
	v_lshl_add_u64 v[4:5], v[2:3], 0, v[4:5]
	global_load_dwordx4 v[14:17], v[4:5], off nt
	v_or_b32_e32 v4, 40, v48
	v_ashrrev_i32_e32 v5, 31, v4
	v_lshlrev_b64 v[4:5], 14, v[4:5]
	v_lshl_add_u64 v[4:5], v[2:3], 0, v[4:5]
	global_load_dwordx4 v[10:13], v[4:5], off nt
	v_or_b32_e32 v4, 48, v48
	v_ashrrev_i32_e32 v5, 31, v4
	v_lshlrev_b64 v[4:5], 14, v[4:5]
	v_lshl_add_u64 v[4:5], v[2:3], 0, v[4:5]
	global_load_dwordx4 v[6:9], v[4:5], off nt
	v_or_b32_e32 v4, 56, v48
	v_lshl_add_u64 v[48:49], v[48:49], 2, s[8:9]
	global_load_dword v48, v[48:49], off
	v_ashrrev_i32_e32 v5, 31, v4
	v_lshlrev_b64 v[4:5], 14, v[4:5]
	v_lshl_add_u64 v[2:3], v[2:3], 0, v[4:5]
	global_load_dwordx4 v[2:5], v[2:3], off nt
	v_or_b32_e32 v202, s2, v34
	v_ashrrev_i32_e32 v203, 31, v202
	v_lshl_add_u64 v[202:203], v[202:203], 2, s[8:9]
	global_load_dword v221, v[202:203], off
	v_or_b32_e32 v204, s2, v35
	v_ashrrev_i32_e32 v205, 31, v204
	v_lshl_add_u64 v[204:205], v[204:205], 2, s[8:9]
	global_load_dword v222, v[204:205], off
	v_or_b32_e32 v206, s2, v36
	v_ashrrev_i32_e32 v207, 31, v206
	v_lshl_add_u64 v[206:207], v[206:207], 2, s[8:9]
	global_load_dword v223, v[206:207], off
	v_or_b32_e32 v208, s2, v37
	v_ashrrev_i32_e32 v209, 31, v208
	v_lshl_add_u64 v[208:209], v[208:209], 2, s[8:9]
	global_load_dword v224, v[208:209], off
	v_or_b32_e32 v210, s2, v38
	v_ashrrev_i32_e32 v211, 31, v210
	v_lshl_add_u64 v[210:211], v[210:211], 2, s[8:9]
	global_load_dword v225, v[210:211], off
	v_or_b32_e32 v212, s2, v39
	v_ashrrev_i32_e32 v213, 31, v212
	v_lshl_add_u64 v[212:213], v[212:213], 2, s[8:9]
	global_load_dword v226, v[212:213], off
	v_or_b32_e32 v214, s2, v40
	v_ashrrev_i32_e32 v215, 31, v214
	v_lshl_add_u64 v[214:215], v[214:215], 2, s[8:9]
	global_load_dword v227, v[214:215], off
	v_add_u32_e32 v43, 0x420, v42
	s_ashr_i32 s3, s2, 31
	s_add_i32 s6, s6, s7
	s_add_i32 s4, s4, s5
	s_cmpk_lt_i32 s6, 0x800
	s_waitcnt vmcnt(8)
	v_pk_mul_f32 v[30:31], v[30:31], v[48:49] op_sel_hi:[1,0]
	v_pk_mul_f32 v[32:33], v[32:33], v[48:49] op_sel_hi:[1,0]
	ds_write2_b32 v42, v30, v31 offset1:1
	ds_write2_b32 v42, v32, v33 offset0:2 offset1:3
	v_or_b32_e32 v30, s2, v34
	v_ashrrev_i32_e32 v31, 31, v30
	v_lshl_add_u64 v[30:31], v[30:31], 2, s[8:9]
	s_waitcnt vmcnt(6)
	v_mov_b32_e32 v32, v221
	s_waitcnt vmcnt(0)
	v_pk_mul_f32 v[30:31], v[46:47], v[32:33] op_sel_hi:[1,0]
	v_pk_mul_f32 v[32:33], v[44:45], v[32:33] op_sel_hi:[1,0]
	ds_write2_b32 v43, v32, v33 offset1:1
	v_add_u32_e32 v32, 0x428, v42
	ds_write2_b32 v32, v30, v31 offset1:1
	v_or_b32_e32 v30, s2, v35
	v_ashrrev_i32_e32 v31, 31, v30
	v_lshl_add_u64 v[30:31], v[30:31], 2, s[8:9]
	s_waitcnt vmcnt(5)
	v_mov_b32_e32 v30, v222
	s_waitcnt vmcnt(0)
	v_pk_mul_f32 v[24:25], v[24:25], v[30:31] op_sel_hi:[1,0]
	v_pk_mul_f32 v[22:23], v[22:23], v[30:31] op_sel_hi:[1,0]
	v_add_u32_e32 v30, 0x840, v42
	ds_write2_b32 v30, v22, v23 offset1:1
	v_add_u32_e32 v22, 0x848, v42
	ds_write2_b32 v22, v24, v25 offset1:1
	v_or_b32_e32 v22, s2, v36
	v_ashrrev_i32_e32 v23, 31, v22
	v_lshl_add_u64 v[22:23], v[22:23], 2, s[8:9]
	s_waitcnt vmcnt(4)
	v_mov_b32_e32 v22, v223
	v_add_u32_e32 v24, s0, v1
	v_ashrrev_i32_e32 v25, 31, v24
	v_lshlrev_b64 v[30:31], 11, v[24:25]
	s_waitcnt vmcnt(0)
; #define LAS __attribute__((address_space(3)))
; __device__ __forceinline__ unsigned pk2(float lo, float hi) { f32x2_t v = {lo, hi}; bf16x2_t b = __builtin_convertvector(v, bf16x2_t); return __builtin_bit_cast(unsigned, b); }
; __device__ __forceinline__ void transpose_item(const float* W, int K, int N, bf16* WT, const float* scale, LAS float* scr, int item, int lane) {
;     ...
;         for (int i = 0; i < 8; ++i) { const int kk = 8 * i + r; f32x4 x = v[i]; if (scale) x = x * scale[k0 + kk];
;             scr[kk * 33 + 4 * q + 0] = x[0]; scr[kk * 33 + 4 * q + 1] = x[1]; scr[kk * 33 + 4 * q + 2] = x[2]; scr[kk * 33 + 4 * q + 3] = x[3]; }
;     }
;     asm volatile("s_waitcnt lgkmcnt(0)" ::: "memory");
;     const int c = lane & 7;
; #pragma unroll
;     for (int j = 0; j < 4; ++j) { const int n = (lane >> 3) + 8 * j; const LAS float* s = scr + (8 * c) * 33 + n;
;         v4u o; o.x = pk2(s[0 * 33], s[1 * 33]); o.y = pk2(s[2 * 33], s[3 * 33]); o.z = pk2(s[4 * 33], s[5 * 33]); o.w = pk2(s[6 * 33], s[7 * 33]);
;         *(v4u*)(WT + (size_t)(n0 + n) * K + k0 + 8 * c) = o; }
	v_pk_mul_f32 v[20:21], v[20:21], v[22:23] op_sel_hi:[1,0]
	v_pk_mul_f32 v[18:19], v[18:19], v[22:23] op_sel_hi:[1,0]
	v_add_u32_e32 v22, 0xc60, v42
	ds_write2_b32 v22, v18, v19 offset1:1
	v_add_u32_e32 v18, 0xc68, v42
	ds_write2_b32 v18, v20, v21 offset1:1
	v_or_b32_e32 v18, s2, v37
	v_ashrrev_i32_e32 v19, 31, v18
	v_lshl_add_u64 v[18:19], v[18:19], 2, s[8:9]
	s_waitcnt vmcnt(3)
	v_mov_b32_e32 v18, v224
	s_waitcnt vmcnt(0)
	v_pk_mul_f32 v[16:17], v[16:17], v[18:19] op_sel_hi:[1,0]
	v_pk_mul_f32 v[14:15], v[14:15], v[18:19] op_sel_hi:[1,0]
	v_add_u32_e32 v18, 0x1080, v42
	ds_write2_b32 v18, v14, v15 offset1:1
	v_add_u32_e32 v14, 0x1088, v42
	ds_write2_b32 v14, v16, v17 offset1:1
	v_or_b32_e32 v14, s2, v38
	v_ashrrev_i32_e32 v15, 31, v14
	v_lshl_add_u64 v[14:15], v[14:15], 2, s[8:9]
	s_waitcnt vmcnt(2)
	v_mov_b32_e32 v14, v225
	s_waitcnt vmcnt(0)
	v_pk_mul_f32 v[12:13], v[12:13], v[14:15] op_sel_hi:[1,0]
	v_pk_mul_f32 v[10:11], v[10:11], v[14:15] op_sel_hi:[1,0]
	v_add_u32_e32 v14, 0x14a0, v42
	ds_write2_b32 v14, v10, v11 offset1:1
	v_add_u32_e32 v10, 0x14a8, v42
	ds_write2_b32 v10, v12, v13 offset1:1
	v_or_b32_e32 v10, s2, v39
	v_ashrrev_i32_e32 v11, 31, v10
	v_lshl_add_u64 v[10:11], v[10:11], 2, s[8:9]
	s_waitcnt vmcnt(1)
	v_mov_b32_e32 v10, v226
	s_waitcnt vmcnt(0)
	v_pk_mul_f32 v[8:9], v[8:9], v[10:11] op_sel_hi:[1,0]
	v_pk_mul_f32 v[6:7], v[6:7], v[10:11] op_sel_hi:[1,0]
	v_add_u32_e32 v10, 0x18c0, v42
	ds_write2_b32 v10, v6, v7 offset1:1
	v_add_u32_e32 v6, 0x18c8, v42
	ds_write2_b32 v6, v8, v9 offset1:1
	v_or_b32_e32 v6, s2, v40
	v_ashrrev_i32_e32 v7, 31, v6
	v_lshl_add_u64 v[6:7], v[6:7], 2, s[8:9]
	s_waitcnt vmcnt(0)
	v_mov_b32_e32 v6, v227
	s_waitcnt vmcnt(0)
	v_pk_mul_f32 v[4:5], v[4:5], v[6:7] op_sel_hi:[1,0]
	v_pk_mul_f32 v[2:3], v[2:3], v[6:7] op_sel_hi:[1,0]
	v_add_u32_e32 v6, 0x1ce0, v42
	ds_write2_b32 v6, v2, v3 offset1:1
	v_add_u32_e32 v2, 0x1ce8, v42
	ds_write2_b32 v2, v4, v5 offset1:1
	s_waitcnt lgkmcnt(0)
	ds_read2_b32 v[8:9], v41 offset0:33 offset1:41
	ds_read2_b32 v[10:11], v41 offset1:8
	ds_read2_b32 v[12:13], v41 offset0:66 offset1:74
	ds_read2_b32 v[14:15], v41 offset0:99 offset1:107
	ds_read2_b32 v[16:17], v41 offset0:132 offset1:140
	ds_read2_b32 v[18:19], v41 offset0:165 offset1:173
	ds_read2_b32 v[20:21], v41 offset0:198 offset1:206
	ds_read2_b32 v[22:23], v41 offset0:231 offset1:239
	v_lshl_add_u64 v[6:7], s[2:3], 1, v[28:29]
	s_waitcnt lgkmcnt(6)
	v_cvt_pk_bf16_f32 v2, v10, v8
	s_waitcnt lgkmcnt(4)
	v_cvt_pk_bf16_f32 v3, v12, v14
	s_waitcnt lgkmcnt(2)
	v_cvt_pk_bf16_f32 v4, v16, v18
	s_waitcnt lgkmcnt(0)
	v_cvt_pk_bf16_f32 v5, v20, v22
	v_lshl_add_u64 v[30:31], v[6:7], 0, v[30:31]
	v_add_u32_e32 v8, 8, v24
	global_store_dwordx4 v[30:31], v[2:5], off nt
	v_add_u32_e32 v30, 16, v24
	v_ashrrev_i32_e32 v31, 31, v30
	v_cvt_pk_bf16_f32 v2, v11, v9
	v_ashrrev_i32_e32 v9, 31, v8
	v_lshlrev_b64 v[8:9], 11, v[8:9]
	v_cvt_pk_bf16_f32 v3, v13, v15
	v_cvt_pk_bf16_f32 v4, v17, v19
	v_cvt_pk_bf16_f32 v5, v21, v23
	v_lshl_add_u64 v[8:9], v[6:7], 0, v[8:9]
	global_store_dwordx4 v[8:9], v[2:5], off nt
	ds_read2_b32 v[8:9], v41 offset0:49 offset1:57
	ds_read2_b32 v[10:11], v41 offset0:16 offset1:24
	ds_read2_b32 v[12:13], v41 offset0:82 offset1:90
	ds_read2_b32 v[14:15], v41 offset0:115 offset1:123
	ds_read2_b32 v[16:17], v41 offset0:148 offset1:156
	ds_read2_b32 v[18:19], v41 offset0:181 offset1:189
	ds_read2_b32 v[20:21], v41 offset0:214 offset1:222
	ds_read2_b32 v[22:23], v41 offset0:247 offset1:255
	v_lshlrev_b64 v[30:31], 11, v[30:31]
	s_waitcnt lgkmcnt(6)
	v_cvt_pk_bf16_f32 v2, v10, v8
	s_waitcnt lgkmcnt(4)
	v_cvt_pk_bf16_f32 v3, v12, v14
	s_waitcnt lgkmcnt(2)
	v_cvt_pk_bf16_f32 v4, v16, v18
	s_waitcnt lgkmcnt(0)
	v_cvt_pk_bf16_f32 v5, v20, v22
	v_lshl_add_u64 v[30:31], v[6:7], 0, v[30:31]
	v_add_u32_e32 v8, 24, v24
	global_store_dwordx4 v[30:31], v[2:5], off nt
	s_nop 1
	v_cvt_pk_bf16_f32 v2, v11, v9
	v_ashrrev_i32_e32 v9, 31, v8
	v_lshlrev_b64 v[8:9], 11, v[8:9]
	v_cvt_pk_bf16_f32 v3, v13, v15
	v_cvt_pk_bf16_f32 v4, v17, v19
	v_cvt_pk_bf16_f32 v5, v21, v23
	v_lshl_add_u64 v[6:7], v[6:7], 0, v[8:9]
	global_store_dwordx4 v[6:7], v[2:5], off nt
	s_waitcnt lgkmcnt(0)
	s_cbranch_scc1 .LBB0_1278
